# P1 tile-order division by the (constant) group size replaced by shift/mask
# speedup vs baseline: 1.0235x; 1.0080x over previous
;     __device__ bool next(int i, Unit& u) const {
;         int t = i, b = 0; if (nb == 3) { t = i / 3; b = i - 3 * t; }
;         const long L = (long)t * G + c; if (L >= nwg) return false;
;         int wgid = (int)L; { const int q = nwg / NXCD, r = nwg % NXCD, xcd = wgid % NXCD, off = wgid / NXCD; wgid = (xcd < r ? xcd * (q + 1) : r * (q + 1) + (xcd - r) * q) + off; }
;         const int nig = WGM * nN, gid = wgid / nig, fm = gid * WGM, gsz = (nM - fm) < WGM ? (nM - fm) : WGM;
;         u.pm = fm + ((wgid % nig) % gsz); u.pn = (wgid % nig) / gsz; u.b = b; return true;
;     }
.LBB0_277:
	s_add_i32 s58, s58, 1
	v_readlane_b32 s6, v253, 5
	s_mul_i32 s6, s58, s6
	s_mul_hi_u32 s14, s58, s96
	s_add_i32 s6, s14, s6
	s_mul_i32 s14, s58, s96
	s_add_u32 s14, s14, s29
	v_readlane_b32 s15, v253, 4
	s_addc_u32 s15, s6, s15
	v_mov_b64_e32 v[0:1], 0x1800
	v_cmp_lt_i64_e64 s[40:41], s[14:15], v[0:1]
	v_mov_b64_e32 v[0:1], 0x17ff
	v_cmp_gt_i64_e32 vcc, s[14:15], v[0:1]
	s_cbranch_vccnz .LBB0_279
	s_ashr_i32 s6, s14, 31
	s_lshr_b32 s6, s6, 29
	s_add_i32 s6, s14, s6
	s_ashr_i32 s15, s6, 3
	s_and_b32 s6, s6, -8
	s_sub_i32 s6, s14, s6
	s_cmp_lt_i32 s6, 0
	s_movk_i32 s14, 0x301
	s_cselect_b32 s14, s14, 0x300
	s_mul_i32 s6, s6, s14
	s_add_i32 s6, s6, s15
	s_mul_hi_i32 s14, s6, 0x2aaaaaab
	s_lshr_b32 s15, s14, 31
	s_ashr_i32 s14, s14, 5
	s_add_i32 s14, s14, s15
	s_lshl_b32 s15, s14, 2
	s_mulk_i32 s14, 0xc0
	s_sub_i32 s6, s6, s14
	s_ashr_i32 s16, s6, 2
	s_and_b32 s6, s6, 3
	s_add_i32 s18, s15, s6
